# group barrier: last arriver skips the polling round trip (its own ticket shows the group is complete)
# speedup vs baseline: 1.0045x; 1.0045x over previous
.LBB0_244:
	s_or_b64 exec, exec, s[6:7]
	s_waitcnt vmcnt(0)
	v_readfirstlane_b32 s4, v1
	s_mov_b32 s8, 0x1000000
	s_nop 0
	v_add_u32_e32 v0, s4, v0
	s_and_b32 s4, s4, 3
	s_cmp_eq_u32 s4, 3
	v_and_b32_e32 v0, -4, v0
	v_add_u32_e32 v0, 4, v0
	s_mov_b64 s[4:5], 0
	s_cbranch_scc1 .LBB0_265
	s_branch .LBB0_254

.LBB0_833:
	s_or_b64 exec, exec, s[12:13]
	s_waitcnt vmcnt(0)
	v_readfirstlane_b32 s6, v1
	s_mov_b32 s8, 0x1000000
	s_nop 0
	v_add_u32_e32 v0, s6, v0
	s_and_b32 s6, s6, 3
	s_cmp_eq_u32 s6, 3
	v_and_b32_e32 v0, -4, v0
	v_add_u32_e32 v0, 4, v0
	s_mov_b64 s[6:7], 0
	s_cbranch_scc1 .LBB0_854
	s_branch .LBB0_843

.LBB0_1121:
	s_or_b64 exec, exec, s[18:19]
	s_waitcnt vmcnt(0)
	v_readfirstlane_b32 s0, v1
	s_mov_b64 s[12:13], 0
	s_nop 0
	v_add_u32_e32 v0, s0, v0
	s_and_b32 s0, s0, 3
	s_cmp_eq_u32 s0, 3
	v_and_b32_e32 v0, -4, v0
	v_add_u32_e32 v0, 4, v0
	s_mov_b32 s0, 0x1000000
	s_cbranch_scc1 .LBB0_1310
	s_branch .LBB0_1299

.LBB0_1339:
	s_or_b64 exec, exec, s[24:25]
	s_waitcnt vmcnt(0)
	v_readfirstlane_b32 s2, v1
	s_mov_b64 s[24:25], 0
	s_nop 0
	v_add_u32_e32 v0, s2, v0
	s_and_b32 s2, s2, 3
	s_cmp_eq_u32 s2, 3
	v_and_b32_e32 v0, -4, v0
	v_add_u32_e32 v0, 4, v0
	s_mov_b32 s2, 0x1000000
	s_cbranch_scc1 .LBB0_1360
	s_branch .LBB0_1349

.LBB0_1472:
	s_or_b64 exec, exec, s[6:7]
	s_waitcnt vmcnt(0)
	v_readfirstlane_b32 s0, v1
	s_mov_b64 s[4:5], 0
	s_nop 0
	v_add_u32_e32 v0, s0, v0
	s_and_b32 s0, s0, 3
	s_cmp_eq_u32 s0, 3
	v_and_b32_e32 v0, -4, v0
	v_add_u32_e32 v0, 4, v0
	s_mov_b32 s0, 0x1000000
	s_cbranch_scc1 .LBB0_1493
	s_branch .LBB0_1482
